# P5 EpiGlu epilogue hand-written: bglu + all 16 YG loads issued up front with counted in-order vmcnt (was 20 serialized vmcnt(0) round trips); same sigmoid op sequence
# baseline (speedup 1.0000x reference)
; __device__ __forceinline__ u32x4 pack8(const f32x4 a, const f32x4 b) { u32x4 w; w.x = cvt_pk_bf16(a[0], a[1]); w.y = cvt_pk_bf16(a[2], a[3]); w.z = cvt_pk_bf16(b[0], b[1]); w.w = cvt_pk_bf16(b[2], b[3]); return w; }
; __device__ __forceinline__ void unpack8(const u32x4 w, f32x4& a, f32x4& b) { a = (f32x4){bf_lo(w.x), bf_hi(w.x), bf_lo(w.y), bf_hi(w.y)}; b = (f32x4){bf_lo(w.z), bf_hi(w.z), bf_lo(w.w), bf_hi(w.w)}; }
; __device__ __forceinline__ float sigmoidf_(float z) { return __builtin_amdgcn_rcpf(1.0f + __builtin_amdgcn_exp2f(-1.44269504089f * z)); }
;     __device__ __forceinline__ void operator()(AccRef acc, const Unit& u, int wr, int wc, int fr, int fq) const {
; #pragma unroll
;         for (int bj = 0; bj < 2; ++bj) { const int col = u.pn * 256 + bj * 128 + wc * 32 + 8 * fq;
;             const f32x4 b0 = *(const f32x4*)(bglu + col), b1 = *(const f32x4*)(bglu + col + 4);
; #pragma unroll
;             for (int ai = 0; ai < 2; ++ai)
; #pragma unroll
;                 for (int m = 0; m < 4; ++m) { const int row = u.pm * 256 + ai * 128 + wr * 64 + m * 16 + fr;
;                     const u32x4 yw = *(const u32x4*)(YG + (size_t)row * DSSM + col); f32x4 y0, y1; unpack8(yw, y0, y1);
;                     const f32x4 z0 = acc[ai][bj][m][0] + b0, z1 = acc[ai][bj][m][1] + b1;
;                     f32x4 o0, o1;
; #pragma unroll
;                     for (int q = 0; q < 4; ++q) { o0[q] = y0[q] * sigmoidf_(z0[q]); o1[q] = y1[q] * sigmoidf_(z1[q]); }
;                     *(u32x4*)(MIX + (size_t)row * D + col) = pack8(o0, o1); } }
.LBB0_605:
	s_mov_b32 s100, s2
	v_lshl_or_b32 v164, s2, 8, v171
	v_ashrrev_i32_e32 v165, 31, v164
	v_lshl_add_u64 v[166:167], v[164:165], 2, s[12:13]
	global_load_dwordx4 v[156:159], v[166:167], off
	global_load_dwordx4 v[160:163], v[166:167], off offset:16
	s_lshl_b32 s2, s16, 8
	v_add_u32_e32 v176, s2, v137
	v_ashrrev_i32_e32 v177, 31, v176
	v_lshlrev_b64 v[164:165], 1, v[164:165]
	v_lshlrev_b64 v[166:167], 11, v[176:177]
	v_lshl_add_u64 v[166:167], s[8:9], 0, v[166:167]
	v_lshl_add_u64 v[166:167], v[166:167], 0, v[164:165]
	v_lshlrev_b64 v[176:177], 12, v[176:177]
	v_lshl_add_u64 v[176:177], s[10:11], 0, v[176:177]
	v_lshl_add_u64 v[176:177], v[176:177], 0, v[164:165]
	global_load_dwordx4 v[178:181], v[166:167], off
	global_load_dwordx4 v[182:185], v[166:167], off offset:256
	s_mov_b64 s[98:99], 0x8000
	v_lshl_add_u64 v[166:167], v[166:167], 0, s[98:99]
	global_load_dwordx4 v[186:189], v[166:167], off
	global_load_dwordx4 v[190:193], v[166:167], off offset:256
	s_mov_b64 s[98:99], 0x8000
	v_lshl_add_u64 v[166:167], v[166:167], 0, s[98:99]
	global_load_dwordx4 v[194:197], v[166:167], off
	global_load_dwordx4 v[198:201], v[166:167], off offset:256
	s_mov_b64 s[98:99], 0x8000
	v_lshl_add_u64 v[166:167], v[166:167], 0, s[98:99]
	global_load_dwordx4 v[202:205], v[166:167], off
	global_load_dwordx4 v[206:209], v[166:167], off offset:256
	s_mov_b64 s[98:99], 0x28000
	v_lshl_add_u64 v[166:167], v[166:167], 0, s[98:99]
	global_load_dwordx4 v[210:213], v[166:167], off
	global_load_dwordx4 v[214:217], v[166:167], off offset:256
	s_mov_b64 s[98:99], 0x8000
	v_lshl_add_u64 v[166:167], v[166:167], 0, s[98:99]
	global_load_dwordx4 v[218:221], v[166:167], off
	global_load_dwordx4 v[222:225], v[166:167], off offset:256
	s_mov_b64 s[98:99], 0x8000
	v_lshl_add_u64 v[166:167], v[166:167], 0, s[98:99]
	global_load_dwordx4 v[226:229], v[166:167], off
	global_load_dwordx4 v[230:233], v[166:167], off offset:256
	s_mov_b64 s[98:99], 0x8000
	v_lshl_add_u64 v[166:167], v[166:167], 0, s[98:99]
	global_load_dwordx4 v[234:237], v[166:167], off
	global_load_dwordx4 v[238:241], v[166:167], off offset:256
	s_waitcnt vmcnt(15)
	v_pk_add_f32 v[132:133], v[132:133], v[156:157]
	v_pk_add_f32 v[134:135], v[134:135], v[158:159]
	v_pk_add_f32 v[128:129], v[128:129], v[160:161]
	v_pk_add_f32 v[130:131], v[130:131], v[162:163]
	v_mul_f32_e32 v132, 0xbfb8aa3b, v132
	v_mul_f32_e32 v133, 0xbfb8aa3b, v133
	v_mul_f32_e32 v134, 0xbfb8aa3b, v134
	v_mul_f32_e32 v135, 0xbfb8aa3b, v135
	v_mul_f32_e32 v128, 0xbfb8aa3b, v128
	v_mul_f32_e32 v129, 0xbfb8aa3b, v129
	v_mul_f32_e32 v130, 0xbfb8aa3b, v130
	v_mul_f32_e32 v131, 0xbfb8aa3b, v131
	v_exp_f32_e32 v132, v132
	v_exp_f32_e32 v133, v133
	v_exp_f32_e32 v134, v134
	v_exp_f32_e32 v135, v135
	v_exp_f32_e32 v128, v128
	v_exp_f32_e32 v129, v129
	v_exp_f32_e32 v130, v130
	v_exp_f32_e32 v131, v131
	v_add_f32_e32 v132, 1.0, v132
	v_add_f32_e32 v133, 1.0, v133
	v_add_f32_e32 v134, 1.0, v134
	v_add_f32_e32 v135, 1.0, v135
	v_add_f32_e32 v128, 1.0, v128
	v_add_f32_e32 v129, 1.0, v129
	v_add_f32_e32 v130, 1.0, v130
	v_add_f32_e32 v131, 1.0, v131
	v_rcp_f32_e32 v132, v132
	v_rcp_f32_e32 v133, v133
	v_rcp_f32_e32 v134, v134
	v_rcp_f32_e32 v135, v135
	v_rcp_f32_e32 v128, v128
	v_rcp_f32_e32 v129, v129
	v_rcp_f32_e32 v130, v130
	v_rcp_f32_e32 v131, v131
	v_lshlrev_b32_e32 v164, 16, v178
	v_lshlrev_b32_e32 v165, 16, v179
	v_lshlrev_b32_e32 v166, 16, v180
	v_lshlrev_b32_e32 v167, 16, v181
	v_and_b32_e32 v178, 0xffff0000, v178
	v_and_b32_e32 v179, 0xffff0000, v179
	v_and_b32_e32 v180, 0xffff0000, v180
	v_and_b32_e32 v181, 0xffff0000, v181
	v_mul_f32_e32 v132, v132, v164
	v_mul_f32_e32 v133, v133, v178
	v_mul_f32_e32 v134, v134, v165
	v_mul_f32_e32 v135, v135, v179
	v_mul_f32_e32 v128, v128, v166
	v_mul_f32_e32 v129, v129, v180
	v_mul_f32_e32 v130, v130, v167
	v_mul_f32_e32 v131, v131, v181
	v_cvt_pk_bf16_f32 v164, v132, v133
	v_cvt_pk_bf16_f32 v165, v134, v135
	v_cvt_pk_bf16_f32 v166, v128, v129
	v_cvt_pk_bf16_f32 v167, v130, v131
	global_store_dwordx4 v[176:177], v[164:167], off
	s_nop 1
	v_lshl_or_b32 v164, s100, 8, v171
	v_ashrrev_i32_e32 v165, 31, v164
	v_lshl_add_u64 v[164:165], v[164:165], 2, s[12:13]
	global_load_dwordx4 v[132:135], v[164:165], off offset:512
	global_load_dwordx4 v[128:131], v[164:165], off offset:528
	s_mov_b64 s[98:99], 0x10000
	v_lshl_add_u64 v[176:177], v[176:177], 0, s[98:99]
	s_waitcnt vmcnt(16)
	v_pk_add_f32 v[124:125], v[124:125], v[156:157]
	v_pk_add_f32 v[126:127], v[126:127], v[158:159]
	v_pk_add_f32 v[120:121], v[120:121], v[160:161]
	v_pk_add_f32 v[122:123], v[122:123], v[162:163]
	v_mul_f32_e32 v124, 0xbfb8aa3b, v124
	v_mul_f32_e32 v125, 0xbfb8aa3b, v125
	v_mul_f32_e32 v126, 0xbfb8aa3b, v126
	v_mul_f32_e32 v127, 0xbfb8aa3b, v127
	v_mul_f32_e32 v120, 0xbfb8aa3b, v120
	v_mul_f32_e32 v121, 0xbfb8aa3b, v121
	v_mul_f32_e32 v122, 0xbfb8aa3b, v122
	v_mul_f32_e32 v123, 0xbfb8aa3b, v123
	v_exp_f32_e32 v124, v124
	v_exp_f32_e32 v125, v125
	v_exp_f32_e32 v126, v126
	v_exp_f32_e32 v127, v127
	v_exp_f32_e32 v120, v120
	v_exp_f32_e32 v121, v121
	v_exp_f32_e32 v122, v122
	v_exp_f32_e32 v123, v123
	v_add_f32_e32 v124, 1.0, v124
	v_add_f32_e32 v125, 1.0, v125
	v_add_f32_e32 v126, 1.0, v126
	v_add_f32_e32 v127, 1.0, v127
	v_add_f32_e32 v120, 1.0, v120
	v_add_f32_e32 v121, 1.0, v121
	v_add_f32_e32 v122, 1.0, v122
	v_add_f32_e32 v123, 1.0, v123
	v_rcp_f32_e32 v124, v124
	v_rcp_f32_e32 v125, v125
	v_rcp_f32_e32 v126, v126
	v_rcp_f32_e32 v127, v127
	v_rcp_f32_e32 v120, v120
	v_rcp_f32_e32 v121, v121
	v_rcp_f32_e32 v122, v122
	v_rcp_f32_e32 v123, v123
	v_lshlrev_b32_e32 v164, 16, v186
	v_lshlrev_b32_e32 v165, 16, v187
	v_lshlrev_b32_e32 v166, 16, v188
	v_lshlrev_b32_e32 v167, 16, v189
	v_and_b32_e32 v186, 0xffff0000, v186
	v_and_b32_e32 v187, 0xffff0000, v187
	v_and_b32_e32 v188, 0xffff0000, v188
	v_and_b32_e32 v189, 0xffff0000, v189
	v_mul_f32_e32 v124, v124, v164
	v_mul_f32_e32 v125, v125, v186
	v_mul_f32_e32 v126, v126, v165
	v_mul_f32_e32 v127, v127, v187
	v_mul_f32_e32 v120, v120, v166
	v_mul_f32_e32 v121, v121, v188
	v_mul_f32_e32 v122, v122, v167
	v_mul_f32_e32 v123, v123, v189
	v_cvt_pk_bf16_f32 v164, v124, v125
	v_cvt_pk_bf16_f32 v165, v126, v127
	v_cvt_pk_bf16_f32 v166, v120, v121
	v_cvt_pk_bf16_f32 v167, v122, v123
	global_store_dwordx4 v[176:177], v[164:167], off
	s_mov_b64 s[98:99], 0x10000
	v_lshl_add_u64 v[176:177], v[176:177], 0, s[98:99]
	s_waitcnt vmcnt(15)
; __device__ __forceinline__ u32x4 pack8(const f32x4 a, const f32x4 b) { u32x4 w; w.x = cvt_pk_bf16(a[0], a[1]); w.y = cvt_pk_bf16(a[2], a[3]); w.z = cvt_pk_bf16(b[0], b[1]); w.w = cvt_pk_bf16(b[2], b[3]); return w; }
; __device__ __forceinline__ void unpack8(const u32x4 w, f32x4& a, f32x4& b) { a = (f32x4){bf_lo(w.x), bf_hi(w.x), bf_lo(w.y), bf_hi(w.y)}; b = (f32x4){bf_lo(w.z), bf_hi(w.z), bf_lo(w.w), bf_hi(w.w)}; }
; __device__ __forceinline__ float sigmoidf_(float z) { return __builtin_amdgcn_rcpf(1.0f + __builtin_amdgcn_exp2f(-1.44269504089f * z)); }
;     __device__ __forceinline__ void operator()(AccRef acc, const Unit& u, int wr, int wc, int fr, int fq) const {
;     ...
;         for (int bj = 0; bj < 2; ++bj) { const int col = u.pn * 256 + bj * 128 + wc * 32 + 8 * fq;
;             const f32x4 b0 = *(const f32x4*)(bglu + col), b1 = *(const f32x4*)(bglu + col + 4);
; #pragma unroll
;             for (int ai = 0; ai < 2; ++ai)
; #pragma unroll
;                 for (int m = 0; m < 4; ++m) { const int row = u.pm * 256 + ai * 128 + wr * 64 + m * 16 + fr;
;                     const u32x4 yw = *(const u32x4*)(YG + (size_t)row * DSSM + col); f32x4 y0, y1; unpack8(yw, y0, y1);
;                     const f32x4 z0 = acc[ai][bj][m][0] + b0, z1 = acc[ai][bj][m][1] + b1;
;                     f32x4 o0, o1;
; #pragma unroll
;                     for (int q = 0; q < 4; ++q) { o0[q] = y0[q] * sigmoidf_(z0[q]); o1[q] = y1[q] * sigmoidf_(z1[q]); }
;                     *(u32x4*)(MIX + (size_t)row * D + col) = pack8(o0, o1); } }
	v_pk_add_f32 v[108:109], v[108:109], v[156:157]
	v_pk_add_f32 v[110:111], v[110:111], v[158:159]
	v_pk_add_f32 v[104:105], v[104:105], v[160:161]
	v_pk_add_f32 v[106:107], v[106:107], v[162:163]
	v_mul_f32_e32 v108, 0xbfb8aa3b, v108
	v_mul_f32_e32 v109, 0xbfb8aa3b, v109
	v_mul_f32_e32 v110, 0xbfb8aa3b, v110
	v_mul_f32_e32 v111, 0xbfb8aa3b, v111
	v_mul_f32_e32 v104, 0xbfb8aa3b, v104
	v_mul_f32_e32 v105, 0xbfb8aa3b, v105
	v_mul_f32_e32 v106, 0xbfb8aa3b, v106
	v_mul_f32_e32 v107, 0xbfb8aa3b, v107
	v_exp_f32_e32 v108, v108
	v_exp_f32_e32 v109, v109
	v_exp_f32_e32 v110, v110
	v_exp_f32_e32 v111, v111
	v_exp_f32_e32 v104, v104
	v_exp_f32_e32 v105, v105
	v_exp_f32_e32 v106, v106
	v_exp_f32_e32 v107, v107
	v_add_f32_e32 v108, 1.0, v108
	v_add_f32_e32 v109, 1.0, v109
	v_add_f32_e32 v110, 1.0, v110
	v_add_f32_e32 v111, 1.0, v111
	v_add_f32_e32 v104, 1.0, v104
	v_add_f32_e32 v105, 1.0, v105
	v_add_f32_e32 v106, 1.0, v106
	v_add_f32_e32 v107, 1.0, v107
	v_rcp_f32_e32 v108, v108
	v_rcp_f32_e32 v109, v109
	v_rcp_f32_e32 v110, v110
	v_rcp_f32_e32 v111, v111
	v_rcp_f32_e32 v104, v104
	v_rcp_f32_e32 v105, v105
	v_rcp_f32_e32 v106, v106
	v_rcp_f32_e32 v107, v107
	v_lshlrev_b32_e32 v164, 16, v194
	v_lshlrev_b32_e32 v165, 16, v195
	v_lshlrev_b32_e32 v166, 16, v196
	v_lshlrev_b32_e32 v167, 16, v197
	v_and_b32_e32 v194, 0xffff0000, v194
	v_and_b32_e32 v195, 0xffff0000, v195
	v_and_b32_e32 v196, 0xffff0000, v196
	v_and_b32_e32 v197, 0xffff0000, v197
	v_mul_f32_e32 v108, v108, v164
	v_mul_f32_e32 v109, v109, v194
	v_mul_f32_e32 v110, v110, v165
	v_mul_f32_e32 v111, v111, v195
	v_mul_f32_e32 v104, v104, v166
	v_mul_f32_e32 v105, v105, v196
	v_mul_f32_e32 v106, v106, v167
	v_mul_f32_e32 v107, v107, v197
	v_cvt_pk_bf16_f32 v164, v108, v109
	v_cvt_pk_bf16_f32 v165, v110, v111
	v_cvt_pk_bf16_f32 v166, v104, v105
	v_cvt_pk_bf16_f32 v167, v106, v107
	global_store_dwordx4 v[176:177], v[164:167], off
	s_mov_b64 s[98:99], 0x10000
	v_lshl_add_u64 v[176:177], v[176:177], 0, s[98:99]
	s_waitcnt vmcnt(14)
	v_pk_add_f32 v[100:101], v[100:101], v[156:157]
	v_pk_add_f32 v[102:103], v[102:103], v[158:159]
	v_pk_add_f32 v[96:97], v[96:97], v[160:161]
	v_pk_add_f32 v[98:99], v[98:99], v[162:163]
	v_mul_f32_e32 v100, 0xbfb8aa3b, v100
	v_mul_f32_e32 v101, 0xbfb8aa3b, v101
	v_mul_f32_e32 v102, 0xbfb8aa3b, v102
	v_mul_f32_e32 v103, 0xbfb8aa3b, v103
	v_mul_f32_e32 v96, 0xbfb8aa3b, v96
	v_mul_f32_e32 v97, 0xbfb8aa3b, v97
	v_mul_f32_e32 v98, 0xbfb8aa3b, v98
	v_mul_f32_e32 v99, 0xbfb8aa3b, v99
	v_exp_f32_e32 v100, v100
	v_exp_f32_e32 v101, v101
	v_exp_f32_e32 v102, v102
	v_exp_f32_e32 v103, v103
	v_exp_f32_e32 v96, v96
	v_exp_f32_e32 v97, v97
	v_exp_f32_e32 v98, v98
	v_exp_f32_e32 v99, v99
	v_add_f32_e32 v100, 1.0, v100
	v_add_f32_e32 v101, 1.0, v101
	v_add_f32_e32 v102, 1.0, v102
	v_add_f32_e32 v103, 1.0, v103
	v_add_f32_e32 v96, 1.0, v96
	v_add_f32_e32 v97, 1.0, v97
	v_add_f32_e32 v98, 1.0, v98
	v_add_f32_e32 v99, 1.0, v99
	v_rcp_f32_e32 v100, v100
	v_rcp_f32_e32 v101, v101
	v_rcp_f32_e32 v102, v102
	v_rcp_f32_e32 v103, v103
	v_rcp_f32_e32 v96, v96
	v_rcp_f32_e32 v97, v97
	v_rcp_f32_e32 v98, v98
	v_rcp_f32_e32 v99, v99
	v_lshlrev_b32_e32 v164, 16, v202
	v_lshlrev_b32_e32 v165, 16, v203
	v_lshlrev_b32_e32 v166, 16, v204
	v_lshlrev_b32_e32 v167, 16, v205
	v_and_b32_e32 v202, 0xffff0000, v202
	v_and_b32_e32 v203, 0xffff0000, v203
	v_and_b32_e32 v204, 0xffff0000, v204
	v_and_b32_e32 v205, 0xffff0000, v205
	v_mul_f32_e32 v100, v100, v164
	v_mul_f32_e32 v101, v101, v202
	v_mul_f32_e32 v102, v102, v165
	v_mul_f32_e32 v103, v103, v203
	v_mul_f32_e32 v96, v96, v166
	v_mul_f32_e32 v97, v97, v204
	v_mul_f32_e32 v98, v98, v167
	v_mul_f32_e32 v99, v99, v205
	v_cvt_pk_bf16_f32 v164, v100, v101
	v_cvt_pk_bf16_f32 v165, v102, v103
	v_cvt_pk_bf16_f32 v166, v96, v97
	v_cvt_pk_bf16_f32 v167, v98, v99
	global_store_dwordx4 v[176:177], v[164:167], off
	s_mov_b64 s[98:99], 0x50000
	v_lshl_add_u64 v[176:177], v[176:177], 0, s[98:99]
	s_waitcnt vmcnt(13)
	v_pk_add_f32 v[92:93], v[92:93], v[156:157]
	v_pk_add_f32 v[94:95], v[94:95], v[158:159]
	v_pk_add_f32 v[88:89], v[88:89], v[160:161]
	v_pk_add_f32 v[90:91], v[90:91], v[162:163]
	v_mul_f32_e32 v92, 0xbfb8aa3b, v92
	v_mul_f32_e32 v93, 0xbfb8aa3b, v93
	v_mul_f32_e32 v94, 0xbfb8aa3b, v94
	v_mul_f32_e32 v95, 0xbfb8aa3b, v95
	v_mul_f32_e32 v88, 0xbfb8aa3b, v88
	v_mul_f32_e32 v89, 0xbfb8aa3b, v89
	v_mul_f32_e32 v90, 0xbfb8aa3b, v90
	v_mul_f32_e32 v91, 0xbfb8aa3b, v91
	v_exp_f32_e32 v92, v92
	v_exp_f32_e32 v93, v93
	v_exp_f32_e32 v94, v94
	v_exp_f32_e32 v95, v95
	v_exp_f32_e32 v88, v88
	v_exp_f32_e32 v89, v89
	v_exp_f32_e32 v90, v90
	v_exp_f32_e32 v91, v91
	v_add_f32_e32 v92, 1.0, v92
	v_add_f32_e32 v93, 1.0, v93
	v_add_f32_e32 v94, 1.0, v94
	v_add_f32_e32 v95, 1.0, v95
	v_add_f32_e32 v88, 1.0, v88
	v_add_f32_e32 v89, 1.0, v89
	v_add_f32_e32 v90, 1.0, v90
	v_add_f32_e32 v91, 1.0, v91
	v_rcp_f32_e32 v92, v92
	v_rcp_f32_e32 v93, v93
	v_rcp_f32_e32 v94, v94
	v_rcp_f32_e32 v95, v95
	v_rcp_f32_e32 v88, v88
	v_rcp_f32_e32 v89, v89
	v_rcp_f32_e32 v90, v90
	v_rcp_f32_e32 v91, v91
	v_lshlrev_b32_e32 v164, 16, v210
	v_lshlrev_b32_e32 v165, 16, v211
	v_lshlrev_b32_e32 v166, 16, v212
	v_lshlrev_b32_e32 v167, 16, v213
	v_and_b32_e32 v210, 0xffff0000, v210
	v_and_b32_e32 v211, 0xffff0000, v211
	v_and_b32_e32 v212, 0xffff0000, v212
	v_and_b32_e32 v213, 0xffff0000, v213
	v_mul_f32_e32 v92, v92, v164
	v_mul_f32_e32 v93, v93, v210
	v_mul_f32_e32 v94, v94, v165
	v_mul_f32_e32 v95, v95, v211
	v_mul_f32_e32 v88, v88, v166
	v_mul_f32_e32 v89, v89, v212
	v_mul_f32_e32 v90, v90, v167
	v_mul_f32_e32 v91, v91, v213
	v_cvt_pk_bf16_f32 v164, v92, v93
	v_cvt_pk_bf16_f32 v165, v94, v95
	v_cvt_pk_bf16_f32 v166, v88, v89
	v_cvt_pk_bf16_f32 v167, v90, v91
	global_store_dwordx4 v[176:177], v[164:167], off
	s_mov_b64 s[98:99], 0x10000
	v_lshl_add_u64 v[176:177], v[176:177], 0, s[98:99]
	s_waitcnt vmcnt(12)
; __device__ __forceinline__ u32x4 pack8(const f32x4 a, const f32x4 b) { u32x4 w; w.x = cvt_pk_bf16(a[0], a[1]); w.y = cvt_pk_bf16(a[2], a[3]); w.z = cvt_pk_bf16(b[0], b[1]); w.w = cvt_pk_bf16(b[2], b[3]); return w; }
; __device__ __forceinline__ void unpack8(const u32x4 w, f32x4& a, f32x4& b) { a = (f32x4){bf_lo(w.x), bf_hi(w.x), bf_lo(w.y), bf_hi(w.y)}; b = (f32x4){bf_lo(w.z), bf_hi(w.z), bf_lo(w.w), bf_hi(w.w)}; }
; __device__ __forceinline__ float sigmoidf_(float z) { return __builtin_amdgcn_rcpf(1.0f + __builtin_amdgcn_exp2f(-1.44269504089f * z)); }
;     __device__ __forceinline__ void operator()(AccRef acc, const Unit& u, int wr, int wc, int fr, int fq) const {
;     ...
;         for (int bj = 0; bj < 2; ++bj) { const int col = u.pn * 256 + bj * 128 + wc * 32 + 8 * fq;
;             const f32x4 b0 = *(const f32x4*)(bglu + col), b1 = *(const f32x4*)(bglu + col + 4);
; #pragma unroll
;             for (int ai = 0; ai < 2; ++ai)
; #pragma unroll
;                 for (int m = 0; m < 4; ++m) { const int row = u.pm * 256 + ai * 128 + wr * 64 + m * 16 + fr;
;                     const u32x4 yw = *(const u32x4*)(YG + (size_t)row * DSSM + col); f32x4 y0, y1; unpack8(yw, y0, y1);
;                     const f32x4 z0 = acc[ai][bj][m][0] + b0, z1 = acc[ai][bj][m][1] + b1;
;                     f32x4 o0, o1;
; #pragma unroll
;                     for (int q = 0; q < 4; ++q) { o0[q] = y0[q] * sigmoidf_(z0[q]); o1[q] = y1[q] * sigmoidf_(z1[q]); }
;                     *(u32x4*)(MIX + (size_t)row * D + col) = pack8(o0, o1); } }
	v_pk_add_f32 v[84:85], v[84:85], v[156:157]
	v_pk_add_f32 v[86:87], v[86:87], v[158:159]
	v_pk_add_f32 v[80:81], v[80:81], v[160:161]
	v_pk_add_f32 v[82:83], v[82:83], v[162:163]
	v_mul_f32_e32 v84, 0xbfb8aa3b, v84
	v_mul_f32_e32 v85, 0xbfb8aa3b, v85
	v_mul_f32_e32 v86, 0xbfb8aa3b, v86
	v_mul_f32_e32 v87, 0xbfb8aa3b, v87
	v_mul_f32_e32 v80, 0xbfb8aa3b, v80
	v_mul_f32_e32 v81, 0xbfb8aa3b, v81
	v_mul_f32_e32 v82, 0xbfb8aa3b, v82
	v_mul_f32_e32 v83, 0xbfb8aa3b, v83
	v_exp_f32_e32 v84, v84
	v_exp_f32_e32 v85, v85
	v_exp_f32_e32 v86, v86
	v_exp_f32_e32 v87, v87
	v_exp_f32_e32 v80, v80
	v_exp_f32_e32 v81, v81
	v_exp_f32_e32 v82, v82
	v_exp_f32_e32 v83, v83
	v_add_f32_e32 v84, 1.0, v84
	v_add_f32_e32 v85, 1.0, v85
	v_add_f32_e32 v86, 1.0, v86
	v_add_f32_e32 v87, 1.0, v87
	v_add_f32_e32 v80, 1.0, v80
	v_add_f32_e32 v81, 1.0, v81
	v_add_f32_e32 v82, 1.0, v82
	v_add_f32_e32 v83, 1.0, v83
	v_rcp_f32_e32 v84, v84
	v_rcp_f32_e32 v85, v85
	v_rcp_f32_e32 v86, v86
	v_rcp_f32_e32 v87, v87
	v_rcp_f32_e32 v80, v80
	v_rcp_f32_e32 v81, v81
	v_rcp_f32_e32 v82, v82
	v_rcp_f32_e32 v83, v83
	v_lshlrev_b32_e32 v164, 16, v218
	v_lshlrev_b32_e32 v165, 16, v219
	v_lshlrev_b32_e32 v166, 16, v220
	v_lshlrev_b32_e32 v167, 16, v221
	v_and_b32_e32 v218, 0xffff0000, v218
	v_and_b32_e32 v219, 0xffff0000, v219
	v_and_b32_e32 v220, 0xffff0000, v220
	v_and_b32_e32 v221, 0xffff0000, v221
	v_mul_f32_e32 v84, v84, v164
	v_mul_f32_e32 v85, v85, v218
	v_mul_f32_e32 v86, v86, v165
	v_mul_f32_e32 v87, v87, v219
	v_mul_f32_e32 v80, v80, v166
	v_mul_f32_e32 v81, v81, v220
	v_mul_f32_e32 v82, v82, v167
	v_mul_f32_e32 v83, v83, v221
	v_cvt_pk_bf16_f32 v164, v84, v85
	v_cvt_pk_bf16_f32 v165, v86, v87
	v_cvt_pk_bf16_f32 v166, v80, v81
	v_cvt_pk_bf16_f32 v167, v82, v83
	global_store_dwordx4 v[176:177], v[164:167], off
	s_mov_b64 s[98:99], 0x10000
	v_lshl_add_u64 v[176:177], v[176:177], 0, s[98:99]
	s_waitcnt vmcnt(11)
	v_pk_add_f32 v[76:77], v[76:77], v[156:157]
	v_pk_add_f32 v[78:79], v[78:79], v[158:159]
	v_pk_add_f32 v[72:73], v[72:73], v[160:161]
	v_pk_add_f32 v[74:75], v[74:75], v[162:163]
	v_mul_f32_e32 v76, 0xbfb8aa3b, v76
	v_mul_f32_e32 v77, 0xbfb8aa3b, v77
	v_mul_f32_e32 v78, 0xbfb8aa3b, v78
	v_mul_f32_e32 v79, 0xbfb8aa3b, v79
	v_mul_f32_e32 v72, 0xbfb8aa3b, v72
	v_mul_f32_e32 v73, 0xbfb8aa3b, v73
	v_mul_f32_e32 v74, 0xbfb8aa3b, v74
	v_mul_f32_e32 v75, 0xbfb8aa3b, v75
	v_exp_f32_e32 v76, v76
	v_exp_f32_e32 v77, v77
	v_exp_f32_e32 v78, v78
	v_exp_f32_e32 v79, v79
	v_exp_f32_e32 v72, v72
	v_exp_f32_e32 v73, v73
	v_exp_f32_e32 v74, v74
	v_exp_f32_e32 v75, v75
	v_add_f32_e32 v76, 1.0, v76
	v_add_f32_e32 v77, 1.0, v77
	v_add_f32_e32 v78, 1.0, v78
	v_add_f32_e32 v79, 1.0, v79
	v_add_f32_e32 v72, 1.0, v72
	v_add_f32_e32 v73, 1.0, v73
	v_add_f32_e32 v74, 1.0, v74
	v_add_f32_e32 v75, 1.0, v75
	v_rcp_f32_e32 v76, v76
	v_rcp_f32_e32 v77, v77
	v_rcp_f32_e32 v78, v78
	v_rcp_f32_e32 v79, v79
	v_rcp_f32_e32 v72, v72
	v_rcp_f32_e32 v73, v73
	v_rcp_f32_e32 v74, v74
	v_rcp_f32_e32 v75, v75
	v_lshlrev_b32_e32 v164, 16, v226
	v_lshlrev_b32_e32 v165, 16, v227
	v_lshlrev_b32_e32 v166, 16, v228
	v_lshlrev_b32_e32 v167, 16, v229
	v_and_b32_e32 v226, 0xffff0000, v226
	v_and_b32_e32 v227, 0xffff0000, v227
	v_and_b32_e32 v228, 0xffff0000, v228
	v_and_b32_e32 v229, 0xffff0000, v229
	v_mul_f32_e32 v76, v76, v164
	v_mul_f32_e32 v77, v77, v226
	v_mul_f32_e32 v78, v78, v165
	v_mul_f32_e32 v79, v79, v227
	v_mul_f32_e32 v72, v72, v166
	v_mul_f32_e32 v73, v73, v228
	v_mul_f32_e32 v74, v74, v167
	v_mul_f32_e32 v75, v75, v229
	v_cvt_pk_bf16_f32 v164, v76, v77
	v_cvt_pk_bf16_f32 v165, v78, v79
	v_cvt_pk_bf16_f32 v166, v72, v73
	v_cvt_pk_bf16_f32 v167, v74, v75
	global_store_dwordx4 v[176:177], v[164:167], off
	s_mov_b64 s[98:99], 0x10000
	v_lshl_add_u64 v[176:177], v[176:177], 0, s[98:99]
	s_waitcnt vmcnt(10)
	v_pk_add_f32 v[68:69], v[68:69], v[156:157]
	v_pk_add_f32 v[70:71], v[70:71], v[158:159]
	v_pk_add_f32 v[64:65], v[64:65], v[160:161]
	v_pk_add_f32 v[66:67], v[66:67], v[162:163]
	v_mul_f32_e32 v68, 0xbfb8aa3b, v68
	v_mul_f32_e32 v69, 0xbfb8aa3b, v69
	v_mul_f32_e32 v70, 0xbfb8aa3b, v70
	v_mul_f32_e32 v71, 0xbfb8aa3b, v71
	v_mul_f32_e32 v64, 0xbfb8aa3b, v64
	v_mul_f32_e32 v65, 0xbfb8aa3b, v65
	v_mul_f32_e32 v66, 0xbfb8aa3b, v66
	v_mul_f32_e32 v67, 0xbfb8aa3b, v67
	v_exp_f32_e32 v68, v68
	v_exp_f32_e32 v69, v69
	v_exp_f32_e32 v70, v70
	v_exp_f32_e32 v71, v71
	v_exp_f32_e32 v64, v64
	v_exp_f32_e32 v65, v65
	v_exp_f32_e32 v66, v66
	v_exp_f32_e32 v67, v67
	v_add_f32_e32 v68, 1.0, v68
	v_add_f32_e32 v69, 1.0, v69
	v_add_f32_e32 v70, 1.0, v70
	v_add_f32_e32 v71, 1.0, v71
	v_add_f32_e32 v64, 1.0, v64
	v_add_f32_e32 v65, 1.0, v65
	v_add_f32_e32 v66, 1.0, v66
	v_add_f32_e32 v67, 1.0, v67
	v_rcp_f32_e32 v68, v68
	v_rcp_f32_e32 v69, v69
	v_rcp_f32_e32 v70, v70
	v_rcp_f32_e32 v71, v71
	v_rcp_f32_e32 v64, v64
	v_rcp_f32_e32 v65, v65
	v_rcp_f32_e32 v66, v66
	v_rcp_f32_e32 v67, v67
	v_lshlrev_b32_e32 v164, 16, v234
	v_lshlrev_b32_e32 v165, 16, v235
	v_lshlrev_b32_e32 v166, 16, v236
	v_lshlrev_b32_e32 v167, 16, v237
	v_and_b32_e32 v234, 0xffff0000, v234
	v_and_b32_e32 v235, 0xffff0000, v235
	v_and_b32_e32 v236, 0xffff0000, v236
	v_and_b32_e32 v237, 0xffff0000, v237
	v_mul_f32_e32 v68, v68, v164
	v_mul_f32_e32 v69, v69, v234
	v_mul_f32_e32 v70, v70, v165
	v_mul_f32_e32 v71, v71, v235
	v_mul_f32_e32 v64, v64, v166
	v_mul_f32_e32 v65, v65, v236
	v_mul_f32_e32 v66, v66, v167
	v_mul_f32_e32 v67, v67, v237
	v_cvt_pk_bf16_f32 v164, v68, v69
	v_cvt_pk_bf16_f32 v165, v70, v71
	v_cvt_pk_bf16_f32 v166, v64, v65
	v_cvt_pk_bf16_f32 v167, v66, v67
	global_store_dwordx4 v[176:177], v[164:167], off
	s_waitcnt vmcnt(7)
; __device__ __forceinline__ u32x4 pack8(const f32x4 a, const f32x4 b) { u32x4 w; w.x = cvt_pk_bf16(a[0], a[1]); w.y = cvt_pk_bf16(a[2], a[3]); w.z = cvt_pk_bf16(b[0], b[1]); w.w = cvt_pk_bf16(b[2], b[3]); return w; }
; __device__ __forceinline__ void unpack8(const u32x4 w, f32x4& a, f32x4& b) { a = (f32x4){bf_lo(w.x), bf_hi(w.x), bf_lo(w.y), bf_hi(w.y)}; b = (f32x4){bf_lo(w.z), bf_hi(w.z), bf_lo(w.w), bf_hi(w.w)}; }
; __device__ __forceinline__ float sigmoidf_(float z) { return __builtin_amdgcn_rcpf(1.0f + __builtin_amdgcn_exp2f(-1.44269504089f * z)); }
;     __device__ __forceinline__ void operator()(AccRef acc, const Unit& u, int wr, int wc, int fr, int fq) const {
;     ...
;         for (int bj = 0; bj < 2; ++bj) { const int col = u.pn * 256 + bj * 128 + wc * 32 + 8 * fq;
;             const f32x4 b0 = *(const f32x4*)(bglu + col), b1 = *(const f32x4*)(bglu + col + 4);
; #pragma unroll
;             for (int ai = 0; ai < 2; ++ai)
; #pragma unroll
;                 for (int m = 0; m < 4; ++m) { const int row = u.pm * 256 + ai * 128 + wr * 64 + m * 16 + fr;
;                     const u32x4 yw = *(const u32x4*)(YG + (size_t)row * DSSM + col); f32x4 y0, y1; unpack8(yw, y0, y1);
;                     const f32x4 z0 = acc[ai][bj][m][0] + b0, z1 = acc[ai][bj][m][1] + b1;
;                     f32x4 o0, o1;
; #pragma unroll
;                     for (int q = 0; q < 4; ++q) { o0[q] = y0[q] * sigmoidf_(z0[q]); o1[q] = y1[q] * sigmoidf_(z1[q]); }
;                     *(u32x4*)(MIX + (size_t)row * D + col) = pack8(o0, o1); } }
	v_pk_add_f32 v[4:5], v[4:5], v[132:133]
	v_pk_add_f32 v[6:7], v[6:7], v[134:135]
	v_pk_add_f32 v[0:1], v[0:1], v[128:129]
	v_pk_add_f32 v[2:3], v[2:3], v[130:131]
	v_mul_f32_e32 v4, 0xbfb8aa3b, v4
	v_mul_f32_e32 v5, 0xbfb8aa3b, v5
	v_mul_f32_e32 v6, 0xbfb8aa3b, v6
	v_mul_f32_e32 v7, 0xbfb8aa3b, v7
	v_mul_f32_e32 v0, 0xbfb8aa3b, v0
	v_mul_f32_e32 v1, 0xbfb8aa3b, v1
	v_mul_f32_e32 v2, 0xbfb8aa3b, v2
	v_mul_f32_e32 v3, 0xbfb8aa3b, v3
	v_exp_f32_e32 v4, v4
	v_exp_f32_e32 v5, v5
	v_exp_f32_e32 v6, v6
	v_exp_f32_e32 v7, v7
	v_exp_f32_e32 v0, v0
	v_exp_f32_e32 v1, v1
	v_exp_f32_e32 v2, v2
	v_exp_f32_e32 v3, v3
	v_add_f32_e32 v4, 1.0, v4
	v_add_f32_e32 v5, 1.0, v5
	v_add_f32_e32 v6, 1.0, v6
	v_add_f32_e32 v7, 1.0, v7
	v_add_f32_e32 v0, 1.0, v0
	v_add_f32_e32 v1, 1.0, v1
	v_add_f32_e32 v2, 1.0, v2
	v_add_f32_e32 v3, 1.0, v3
	v_rcp_f32_e32 v4, v4
	v_rcp_f32_e32 v5, v5
	v_rcp_f32_e32 v6, v6
	v_rcp_f32_e32 v7, v7
	v_rcp_f32_e32 v0, v0
	v_rcp_f32_e32 v1, v1
	v_rcp_f32_e32 v2, v2
	v_rcp_f32_e32 v3, v3
	v_lshlrev_b32_e32 v164, 16, v238
	v_lshlrev_b32_e32 v165, 16, v239
	v_lshlrev_b32_e32 v166, 16, v240
	v_lshlrev_b32_e32 v167, 16, v241
	v_and_b32_e32 v238, 0xffff0000, v238
	v_and_b32_e32 v239, 0xffff0000, v239
	v_and_b32_e32 v240, 0xffff0000, v240
	v_and_b32_e32 v241, 0xffff0000, v241
	v_mul_f32_e32 v4, v4, v164
	v_mul_f32_e32 v5, v5, v238
	v_mul_f32_e32 v6, v6, v165
	v_mul_f32_e32 v7, v7, v239
	v_mul_f32_e32 v0, v0, v166
	v_mul_f32_e32 v1, v1, v240
	v_mul_f32_e32 v2, v2, v167
	v_mul_f32_e32 v3, v3, v241
	v_cvt_pk_bf16_f32 v164, v4, v5
	v_cvt_pk_bf16_f32 v165, v6, v7
	v_cvt_pk_bf16_f32 v166, v0, v1
	v_cvt_pk_bf16_f32 v167, v2, v3
	global_store_dwordx4 v[176:177], v[164:167], off offset:256
	s_mov_b32 s98, 0xffff0000
	s_mov_b32 s99, -1
	v_lshl_add_u64 v[176:177], v[176:177], 0, s[98:99]
	v_pk_add_f32 v[12:13], v[12:13], v[132:133]
	v_pk_add_f32 v[14:15], v[14:15], v[134:135]
	v_pk_add_f32 v[8:9], v[8:9], v[128:129]
	v_pk_add_f32 v[10:11], v[10:11], v[130:131]
	v_mul_f32_e32 v12, 0xbfb8aa3b, v12
	v_mul_f32_e32 v13, 0xbfb8aa3b, v13
	v_mul_f32_e32 v14, 0xbfb8aa3b, v14
	v_mul_f32_e32 v15, 0xbfb8aa3b, v15
	v_mul_f32_e32 v8, 0xbfb8aa3b, v8
	v_mul_f32_e32 v9, 0xbfb8aa3b, v9
	v_mul_f32_e32 v10, 0xbfb8aa3b, v10
	v_mul_f32_e32 v11, 0xbfb8aa3b, v11
	v_exp_f32_e32 v12, v12
	v_exp_f32_e32 v13, v13
	v_exp_f32_e32 v14, v14
	v_exp_f32_e32 v15, v15
	v_exp_f32_e32 v8, v8
	v_exp_f32_e32 v9, v9
	v_exp_f32_e32 v10, v10
	v_exp_f32_e32 v11, v11
	v_add_f32_e32 v12, 1.0, v12
	v_add_f32_e32 v13, 1.0, v13
	v_add_f32_e32 v14, 1.0, v14
	v_add_f32_e32 v15, 1.0, v15
	v_add_f32_e32 v8, 1.0, v8
	v_add_f32_e32 v9, 1.0, v9
	v_add_f32_e32 v10, 1.0, v10
	v_add_f32_e32 v11, 1.0, v11
	v_rcp_f32_e32 v12, v12
	v_rcp_f32_e32 v13, v13
	v_rcp_f32_e32 v14, v14
	v_rcp_f32_e32 v15, v15
	v_rcp_f32_e32 v8, v8
	v_rcp_f32_e32 v9, v9
	v_rcp_f32_e32 v10, v10
	v_rcp_f32_e32 v11, v11
	v_lshlrev_b32_e32 v164, 16, v230
	v_lshlrev_b32_e32 v165, 16, v231
	v_lshlrev_b32_e32 v166, 16, v232
	v_lshlrev_b32_e32 v167, 16, v233
	v_and_b32_e32 v230, 0xffff0000, v230
	v_and_b32_e32 v231, 0xffff0000, v231
	v_and_b32_e32 v232, 0xffff0000, v232
	v_and_b32_e32 v233, 0xffff0000, v233
	v_mul_f32_e32 v12, v12, v164
	v_mul_f32_e32 v13, v13, v230
	v_mul_f32_e32 v14, v14, v165
	v_mul_f32_e32 v15, v15, v231
	v_mul_f32_e32 v8, v8, v166
	v_mul_f32_e32 v9, v9, v232
	v_mul_f32_e32 v10, v10, v167
	v_mul_f32_e32 v11, v11, v233
	v_cvt_pk_bf16_f32 v164, v12, v13
	v_cvt_pk_bf16_f32 v165, v14, v15
	v_cvt_pk_bf16_f32 v166, v8, v9
	v_cvt_pk_bf16_f32 v167, v10, v11
	global_store_dwordx4 v[176:177], v[164:167], off offset:256
	s_mov_b32 s98, 0xffff0000
	s_mov_b32 s99, -1
	v_lshl_add_u64 v[176:177], v[176:177], 0, s[98:99]
	v_pk_add_f32 v[20:21], v[20:21], v[132:133]
	v_pk_add_f32 v[22:23], v[22:23], v[134:135]
	v_pk_add_f32 v[16:17], v[16:17], v[128:129]
	v_pk_add_f32 v[18:19], v[18:19], v[130:131]
	v_mul_f32_e32 v20, 0xbfb8aa3b, v20
	v_mul_f32_e32 v21, 0xbfb8aa3b, v21
	v_mul_f32_e32 v22, 0xbfb8aa3b, v22
	v_mul_f32_e32 v23, 0xbfb8aa3b, v23
	v_mul_f32_e32 v16, 0xbfb8aa3b, v16
	v_mul_f32_e32 v17, 0xbfb8aa3b, v17
	v_mul_f32_e32 v18, 0xbfb8aa3b, v18
	v_mul_f32_e32 v19, 0xbfb8aa3b, v19
	v_exp_f32_e32 v20, v20
	v_exp_f32_e32 v21, v21
	v_exp_f32_e32 v22, v22
	v_exp_f32_e32 v23, v23
	v_exp_f32_e32 v16, v16
	v_exp_f32_e32 v17, v17
	v_exp_f32_e32 v18, v18
	v_exp_f32_e32 v19, v19
	v_add_f32_e32 v20, 1.0, v20
	v_add_f32_e32 v21, 1.0, v21
	v_add_f32_e32 v22, 1.0, v22
	v_add_f32_e32 v23, 1.0, v23
	v_add_f32_e32 v16, 1.0, v16
	v_add_f32_e32 v17, 1.0, v17
	v_add_f32_e32 v18, 1.0, v18
	v_add_f32_e32 v19, 1.0, v19
	v_rcp_f32_e32 v20, v20
	v_rcp_f32_e32 v21, v21
	v_rcp_f32_e32 v22, v22
	v_rcp_f32_e32 v23, v23
	v_rcp_f32_e32 v16, v16
	v_rcp_f32_e32 v17, v17
	v_rcp_f32_e32 v18, v18
	v_rcp_f32_e32 v19, v19
	v_lshlrev_b32_e32 v164, 16, v222
	v_lshlrev_b32_e32 v165, 16, v223
	v_lshlrev_b32_e32 v166, 16, v224
	v_lshlrev_b32_e32 v167, 16, v225
	v_and_b32_e32 v222, 0xffff0000, v222
	v_and_b32_e32 v223, 0xffff0000, v223
	v_and_b32_e32 v224, 0xffff0000, v224
	v_and_b32_e32 v225, 0xffff0000, v225
	v_mul_f32_e32 v20, v20, v164
	v_mul_f32_e32 v21, v21, v222
	v_mul_f32_e32 v22, v22, v165
	v_mul_f32_e32 v23, v23, v223
	v_mul_f32_e32 v16, v16, v166
	v_mul_f32_e32 v17, v17, v224
	v_mul_f32_e32 v18, v18, v167
	v_mul_f32_e32 v19, v19, v225
	v_cvt_pk_bf16_f32 v164, v20, v21
	v_cvt_pk_bf16_f32 v165, v22, v23
	v_cvt_pk_bf16_f32 v166, v16, v17
	v_cvt_pk_bf16_f32 v167, v18, v19
	global_store_dwordx4 v[176:177], v[164:167], off offset:256
	s_mov_b32 s98, 0xffff0000
	s_mov_b32 s99, -1
	v_lshl_add_u64 v[176:177], v[176:177], 0, s[98:99]
	v_pk_add_f32 v[28:29], v[28:29], v[132:133]
; __device__ __forceinline__ u32x4 pack8(const f32x4 a, const f32x4 b) { u32x4 w; w.x = cvt_pk_bf16(a[0], a[1]); w.y = cvt_pk_bf16(a[2], a[3]); w.z = cvt_pk_bf16(b[0], b[1]); w.w = cvt_pk_bf16(b[2], b[3]); return w; }
; __device__ __forceinline__ void unpack8(const u32x4 w, f32x4& a, f32x4& b) { a = (f32x4){bf_lo(w.x), bf_hi(w.x), bf_lo(w.y), bf_hi(w.y)}; b = (f32x4){bf_lo(w.z), bf_hi(w.z), bf_lo(w.w), bf_hi(w.w)}; }
; __device__ __forceinline__ float sigmoidf_(float z) { return __builtin_amdgcn_rcpf(1.0f + __builtin_amdgcn_exp2f(-1.44269504089f * z)); }
;     __device__ __forceinline__ void operator()(AccRef acc, const Unit& u, int wr, int wc, int fr, int fq) const {
;     ...
;                 for (int m = 0; m < 4; ++m) { const int row = u.pm * 256 + ai * 128 + wr * 64 + m * 16 + fr;
;                     const u32x4 yw = *(const u32x4*)(YG + (size_t)row * DSSM + col); f32x4 y0, y1; unpack8(yw, y0, y1);
;                     const f32x4 z0 = acc[ai][bj][m][0] + b0, z1 = acc[ai][bj][m][1] + b1;
;                     f32x4 o0, o1;
; #pragma unroll
;                     for (int q = 0; q < 4; ++q) { o0[q] = y0[q] * sigmoidf_(z0[q]); o1[q] = y1[q] * sigmoidf_(z1[q]); }
;                     *(u32x4*)(MIX + (size_t)row * D + col) = pack8(o0, o1); } }
	v_pk_add_f32 v[30:31], v[30:31], v[134:135]
	v_pk_add_f32 v[24:25], v[24:25], v[128:129]
	v_pk_add_f32 v[26:27], v[26:27], v[130:131]
	v_mul_f32_e32 v28, 0xbfb8aa3b, v28
	v_mul_f32_e32 v29, 0xbfb8aa3b, v29
	v_mul_f32_e32 v30, 0xbfb8aa3b, v30
	v_mul_f32_e32 v31, 0xbfb8aa3b, v31
	v_mul_f32_e32 v24, 0xbfb8aa3b, v24
	v_mul_f32_e32 v25, 0xbfb8aa3b, v25
	v_mul_f32_e32 v26, 0xbfb8aa3b, v26
	v_mul_f32_e32 v27, 0xbfb8aa3b, v27
	v_exp_f32_e32 v28, v28
	v_exp_f32_e32 v29, v29
	v_exp_f32_e32 v30, v30
	v_exp_f32_e32 v31, v31
	v_exp_f32_e32 v24, v24
	v_exp_f32_e32 v25, v25
	v_exp_f32_e32 v26, v26
	v_exp_f32_e32 v27, v27
	v_add_f32_e32 v28, 1.0, v28
	v_add_f32_e32 v29, 1.0, v29
	v_add_f32_e32 v30, 1.0, v30
	v_add_f32_e32 v31, 1.0, v31
	v_add_f32_e32 v24, 1.0, v24
	v_add_f32_e32 v25, 1.0, v25
	v_add_f32_e32 v26, 1.0, v26
	v_add_f32_e32 v27, 1.0, v27
	v_rcp_f32_e32 v28, v28
	v_rcp_f32_e32 v29, v29
	v_rcp_f32_e32 v30, v30
	v_rcp_f32_e32 v31, v31
	v_rcp_f32_e32 v24, v24
	v_rcp_f32_e32 v25, v25
	v_rcp_f32_e32 v26, v26
	v_rcp_f32_e32 v27, v27
	v_lshlrev_b32_e32 v164, 16, v214
	v_lshlrev_b32_e32 v165, 16, v215
	v_lshlrev_b32_e32 v166, 16, v216
	v_lshlrev_b32_e32 v167, 16, v217
	v_and_b32_e32 v214, 0xffff0000, v214
	v_and_b32_e32 v215, 0xffff0000, v215
	v_and_b32_e32 v216, 0xffff0000, v216
	v_and_b32_e32 v217, 0xffff0000, v217
	v_mul_f32_e32 v28, v28, v164
	v_mul_f32_e32 v29, v29, v214
	v_mul_f32_e32 v30, v30, v165
	v_mul_f32_e32 v31, v31, v215
	v_mul_f32_e32 v24, v24, v166
	v_mul_f32_e32 v25, v25, v216
	v_mul_f32_e32 v26, v26, v167
	v_mul_f32_e32 v27, v27, v217
	v_cvt_pk_bf16_f32 v164, v28, v29
	v_cvt_pk_bf16_f32 v165, v30, v31
	v_cvt_pk_bf16_f32 v166, v24, v25
	v_cvt_pk_bf16_f32 v167, v26, v27
	global_store_dwordx4 v[176:177], v[164:167], off offset:256
	s_mov_b32 s98, 0xfffb0000
	s_mov_b32 s99, -1
	v_lshl_add_u64 v[176:177], v[176:177], 0, s[98:99]
	v_pk_add_f32 v[36:37], v[36:37], v[132:133]
	v_pk_add_f32 v[38:39], v[38:39], v[134:135]
	v_pk_add_f32 v[32:33], v[32:33], v[128:129]
	v_pk_add_f32 v[34:35], v[34:35], v[130:131]
	v_mul_f32_e32 v36, 0xbfb8aa3b, v36
	v_mul_f32_e32 v37, 0xbfb8aa3b, v37
	v_mul_f32_e32 v38, 0xbfb8aa3b, v38
	v_mul_f32_e32 v39, 0xbfb8aa3b, v39
	v_mul_f32_e32 v32, 0xbfb8aa3b, v32
	v_mul_f32_e32 v33, 0xbfb8aa3b, v33
	v_mul_f32_e32 v34, 0xbfb8aa3b, v34
	v_mul_f32_e32 v35, 0xbfb8aa3b, v35
	v_exp_f32_e32 v36, v36
	v_exp_f32_e32 v37, v37
	v_exp_f32_e32 v38, v38
	v_exp_f32_e32 v39, v39
	v_exp_f32_e32 v32, v32
	v_exp_f32_e32 v33, v33
	v_exp_f32_e32 v34, v34
	v_exp_f32_e32 v35, v35
	v_add_f32_e32 v36, 1.0, v36
	v_add_f32_e32 v37, 1.0, v37
	v_add_f32_e32 v38, 1.0, v38
	v_add_f32_e32 v39, 1.0, v39
	v_add_f32_e32 v32, 1.0, v32
	v_add_f32_e32 v33, 1.0, v33
	v_add_f32_e32 v34, 1.0, v34
	v_add_f32_e32 v35, 1.0, v35
	v_rcp_f32_e32 v36, v36
	v_rcp_f32_e32 v37, v37
	v_rcp_f32_e32 v38, v38
	v_rcp_f32_e32 v39, v39
	v_rcp_f32_e32 v32, v32
	v_rcp_f32_e32 v33, v33
	v_rcp_f32_e32 v34, v34
	v_rcp_f32_e32 v35, v35
	v_lshlrev_b32_e32 v164, 16, v206
	v_lshlrev_b32_e32 v165, 16, v207
	v_lshlrev_b32_e32 v166, 16, v208
	v_lshlrev_b32_e32 v167, 16, v209
	v_and_b32_e32 v206, 0xffff0000, v206
	v_and_b32_e32 v207, 0xffff0000, v207
	v_and_b32_e32 v208, 0xffff0000, v208
	v_and_b32_e32 v209, 0xffff0000, v209
	v_mul_f32_e32 v36, v36, v164
	v_mul_f32_e32 v37, v37, v206
	v_mul_f32_e32 v38, v38, v165
	v_mul_f32_e32 v39, v39, v207
	v_mul_f32_e32 v32, v32, v166
	v_mul_f32_e32 v33, v33, v208
	v_mul_f32_e32 v34, v34, v167
	v_mul_f32_e32 v35, v35, v209
	v_cvt_pk_bf16_f32 v164, v36, v37
	v_cvt_pk_bf16_f32 v165, v38, v39
	v_cvt_pk_bf16_f32 v166, v32, v33
	v_cvt_pk_bf16_f32 v167, v34, v35
	global_store_dwordx4 v[176:177], v[164:167], off offset:256
	s_mov_b32 s98, 0xffff0000
	s_mov_b32 s99, -1
	v_lshl_add_u64 v[176:177], v[176:177], 0, s[98:99]
	v_pk_add_f32 v[44:45], v[44:45], v[132:133]
	v_pk_add_f32 v[46:47], v[46:47], v[134:135]
	v_pk_add_f32 v[40:41], v[40:41], v[128:129]
	v_pk_add_f32 v[42:43], v[42:43], v[130:131]
	v_mul_f32_e32 v44, 0xbfb8aa3b, v44
	v_mul_f32_e32 v45, 0xbfb8aa3b, v45
	v_mul_f32_e32 v46, 0xbfb8aa3b, v46
	v_mul_f32_e32 v47, 0xbfb8aa3b, v47
	v_mul_f32_e32 v40, 0xbfb8aa3b, v40
	v_mul_f32_e32 v41, 0xbfb8aa3b, v41
	v_mul_f32_e32 v42, 0xbfb8aa3b, v42
	v_mul_f32_e32 v43, 0xbfb8aa3b, v43
	v_exp_f32_e32 v44, v44
	v_exp_f32_e32 v45, v45
	v_exp_f32_e32 v46, v46
	v_exp_f32_e32 v47, v47
	v_exp_f32_e32 v40, v40
	v_exp_f32_e32 v41, v41
	v_exp_f32_e32 v42, v42
	v_exp_f32_e32 v43, v43
	v_add_f32_e32 v44, 1.0, v44
	v_add_f32_e32 v45, 1.0, v45
	v_add_f32_e32 v46, 1.0, v46
	v_add_f32_e32 v47, 1.0, v47
	v_add_f32_e32 v40, 1.0, v40
	v_add_f32_e32 v41, 1.0, v41
	v_add_f32_e32 v42, 1.0, v42
	v_add_f32_e32 v43, 1.0, v43
	v_rcp_f32_e32 v44, v44
	v_rcp_f32_e32 v45, v45
	v_rcp_f32_e32 v46, v46
	v_rcp_f32_e32 v47, v47
	v_rcp_f32_e32 v40, v40
	v_rcp_f32_e32 v41, v41
	v_rcp_f32_e32 v42, v42
	v_rcp_f32_e32 v43, v43
	v_lshlrev_b32_e32 v164, 16, v198
	v_lshlrev_b32_e32 v165, 16, v199
; __device__ __forceinline__ u32x4 pack8(const f32x4 a, const f32x4 b) { u32x4 w; w.x = cvt_pk_bf16(a[0], a[1]); w.y = cvt_pk_bf16(a[2], a[3]); w.z = cvt_pk_bf16(b[0], b[1]); w.w = cvt_pk_bf16(b[2], b[3]); return w; }
; __device__ __forceinline__ void unpack8(const u32x4 w, f32x4& a, f32x4& b) { a = (f32x4){bf_lo(w.x), bf_hi(w.x), bf_lo(w.y), bf_hi(w.y)}; b = (f32x4){bf_lo(w.z), bf_hi(w.z), bf_lo(w.w), bf_hi(w.w)}; }
; __device__ __forceinline__ float sigmoidf_(float z) { return __builtin_amdgcn_rcpf(1.0f + __builtin_amdgcn_exp2f(-1.44269504089f * z)); }
;     __device__ __forceinline__ void operator()(AccRef acc, const Unit& u, int wr, int wc, int fr, int fq) const {
;     ...
;                 for (int m = 0; m < 4; ++m) { const int row = u.pm * 256 + ai * 128 + wr * 64 + m * 16 + fr;
;                     const u32x4 yw = *(const u32x4*)(YG + (size_t)row * DSSM + col); f32x4 y0, y1; unpack8(yw, y0, y1);
;                     const f32x4 z0 = acc[ai][bj][m][0] + b0, z1 = acc[ai][bj][m][1] + b1;
;                     f32x4 o0, o1;
; #pragma unroll
;                     for (int q = 0; q < 4; ++q) { o0[q] = y0[q] * sigmoidf_(z0[q]); o1[q] = y1[q] * sigmoidf_(z1[q]); }
;                     *(u32x4*)(MIX + (size_t)row * D + col) = pack8(o0, o1); } }
;         if (u.pm >= 128) {
;             asm volatile("s_waitcnt vmcnt(0)" ::: "memory"); __builtin_amdgcn_fence(__ATOMIC_RELEASE, "agent"); asm volatile("s_waitcnt vmcnt(0)" ::: "memory");
;             if (fr + 16 * fq == 0) __hip_atomic_fetch_add(flag, 1u, __ATOMIC_RELAXED, __HIP_MEMORY_SCOPE_AGENT); }
	v_lshlrev_b32_e32 v166, 16, v200
	v_lshlrev_b32_e32 v167, 16, v201
	v_and_b32_e32 v198, 0xffff0000, v198
	v_and_b32_e32 v199, 0xffff0000, v199
	v_and_b32_e32 v200, 0xffff0000, v200
	v_and_b32_e32 v201, 0xffff0000, v201
	v_mul_f32_e32 v44, v44, v164
	v_mul_f32_e32 v45, v45, v198
	v_mul_f32_e32 v46, v46, v165
	v_mul_f32_e32 v47, v47, v199
	v_mul_f32_e32 v40, v40, v166
	v_mul_f32_e32 v41, v41, v200
	v_mul_f32_e32 v42, v42, v167
	v_mul_f32_e32 v43, v43, v201
	v_cvt_pk_bf16_f32 v164, v44, v45
	v_cvt_pk_bf16_f32 v165, v46, v47
	v_cvt_pk_bf16_f32 v166, v40, v41
	v_cvt_pk_bf16_f32 v167, v42, v43
	global_store_dwordx4 v[176:177], v[164:167], off offset:256
	s_mov_b32 s98, 0xffff0000
	s_mov_b32 s99, -1
	v_lshl_add_u64 v[176:177], v[176:177], 0, s[98:99]
	v_pk_add_f32 v[52:53], v[52:53], v[132:133]
	v_pk_add_f32 v[54:55], v[54:55], v[134:135]
	v_pk_add_f32 v[48:49], v[48:49], v[128:129]
	v_pk_add_f32 v[50:51], v[50:51], v[130:131]
	v_mul_f32_e32 v52, 0xbfb8aa3b, v52
	v_mul_f32_e32 v53, 0xbfb8aa3b, v53
	v_mul_f32_e32 v54, 0xbfb8aa3b, v54
	v_mul_f32_e32 v55, 0xbfb8aa3b, v55
	v_mul_f32_e32 v48, 0xbfb8aa3b, v48
	v_mul_f32_e32 v49, 0xbfb8aa3b, v49
	v_mul_f32_e32 v50, 0xbfb8aa3b, v50
	v_mul_f32_e32 v51, 0xbfb8aa3b, v51
	v_exp_f32_e32 v52, v52
	v_exp_f32_e32 v53, v53
	v_exp_f32_e32 v54, v54
	v_exp_f32_e32 v55, v55
	v_exp_f32_e32 v48, v48
	v_exp_f32_e32 v49, v49
	v_exp_f32_e32 v50, v50
	v_exp_f32_e32 v51, v51
	v_add_f32_e32 v52, 1.0, v52
	v_add_f32_e32 v53, 1.0, v53
	v_add_f32_e32 v54, 1.0, v54
	v_add_f32_e32 v55, 1.0, v55
	v_add_f32_e32 v48, 1.0, v48
	v_add_f32_e32 v49, 1.0, v49
	v_add_f32_e32 v50, 1.0, v50
	v_add_f32_e32 v51, 1.0, v51
	v_rcp_f32_e32 v52, v52
	v_rcp_f32_e32 v53, v53
	v_rcp_f32_e32 v54, v54
	v_rcp_f32_e32 v55, v55
	v_rcp_f32_e32 v48, v48
	v_rcp_f32_e32 v49, v49
	v_rcp_f32_e32 v50, v50
	v_rcp_f32_e32 v51, v51
	v_lshlrev_b32_e32 v164, 16, v190
	v_lshlrev_b32_e32 v165, 16, v191
	v_lshlrev_b32_e32 v166, 16, v192
	v_lshlrev_b32_e32 v167, 16, v193
	v_and_b32_e32 v190, 0xffff0000, v190
	v_and_b32_e32 v191, 0xffff0000, v191
	v_and_b32_e32 v192, 0xffff0000, v192
	v_and_b32_e32 v193, 0xffff0000, v193
	v_mul_f32_e32 v52, v52, v164
	v_mul_f32_e32 v53, v53, v190
	v_mul_f32_e32 v54, v54, v165
	v_mul_f32_e32 v55, v55, v191
	v_mul_f32_e32 v48, v48, v166
	v_mul_f32_e32 v49, v49, v192
	v_mul_f32_e32 v50, v50, v167
	v_mul_f32_e32 v51, v51, v193
	v_cvt_pk_bf16_f32 v164, v52, v53
	v_cvt_pk_bf16_f32 v165, v54, v55
	v_cvt_pk_bf16_f32 v166, v48, v49
	v_cvt_pk_bf16_f32 v167, v50, v51
	global_store_dwordx4 v[176:177], v[164:167], off offset:256
	s_mov_b32 s98, 0xffff0000
	s_mov_b32 s99, -1
	v_lshl_add_u64 v[176:177], v[176:177], 0, s[98:99]
	v_pk_add_f32 v[60:61], v[60:61], v[132:133]
	v_pk_add_f32 v[62:63], v[62:63], v[134:135]
	v_pk_add_f32 v[56:57], v[56:57], v[128:129]
	v_pk_add_f32 v[58:59], v[58:59], v[130:131]
	v_mul_f32_e32 v60, 0xbfb8aa3b, v60
	v_mul_f32_e32 v61, 0xbfb8aa3b, v61
	v_mul_f32_e32 v62, 0xbfb8aa3b, v62
	v_mul_f32_e32 v63, 0xbfb8aa3b, v63
	v_mul_f32_e32 v56, 0xbfb8aa3b, v56
	v_mul_f32_e32 v57, 0xbfb8aa3b, v57
	v_mul_f32_e32 v58, 0xbfb8aa3b, v58
	v_mul_f32_e32 v59, 0xbfb8aa3b, v59
	v_exp_f32_e32 v60, v60
	v_exp_f32_e32 v61, v61
	v_exp_f32_e32 v62, v62
	v_exp_f32_e32 v63, v63
	v_exp_f32_e32 v56, v56
	v_exp_f32_e32 v57, v57
	v_exp_f32_e32 v58, v58
	v_exp_f32_e32 v59, v59
	v_add_f32_e32 v60, 1.0, v60
	v_add_f32_e32 v61, 1.0, v61
	v_add_f32_e32 v62, 1.0, v62
	v_add_f32_e32 v63, 1.0, v63
	v_add_f32_e32 v56, 1.0, v56
	v_add_f32_e32 v57, 1.0, v57
	v_add_f32_e32 v58, 1.0, v58
	v_add_f32_e32 v59, 1.0, v59
	v_rcp_f32_e32 v60, v60
	v_rcp_f32_e32 v61, v61
	v_rcp_f32_e32 v62, v62
	v_rcp_f32_e32 v63, v63
	v_rcp_f32_e32 v56, v56
	v_rcp_f32_e32 v57, v57
	v_rcp_f32_e32 v58, v58
	v_rcp_f32_e32 v59, v59
	v_lshlrev_b32_e32 v164, 16, v182
	v_lshlrev_b32_e32 v165, 16, v183
	v_lshlrev_b32_e32 v166, 16, v184
	v_lshlrev_b32_e32 v167, 16, v185
	v_and_b32_e32 v182, 0xffff0000, v182
	v_and_b32_e32 v183, 0xffff0000, v183
	v_and_b32_e32 v184, 0xffff0000, v184
	v_and_b32_e32 v185, 0xffff0000, v185
	v_mul_f32_e32 v60, v60, v164
	v_mul_f32_e32 v61, v61, v182
	v_mul_f32_e32 v62, v62, v165
	v_mul_f32_e32 v63, v63, v183
	v_mul_f32_e32 v56, v56, v166
	v_mul_f32_e32 v57, v57, v184
	v_mul_f32_e32 v58, v58, v167
	v_mul_f32_e32 v59, v59, v185
	v_cvt_pk_bf16_f32 v164, v60, v61
	v_cvt_pk_bf16_f32 v165, v62, v63
	v_cvt_pk_bf16_f32 v166, v56, v57
	v_cvt_pk_bf16_f32 v167, v58, v59
	global_store_dwordx4 v[176:177], v[164:167], off offset:256
	s_cmpk_lt_i32 s16, 0x80
	s_cbranch_scc1 .LBB0_610
	s_waitcnt vmcnt(0)
	buffer_wbl2 sc1
	s_waitcnt vmcnt(0)
	s_waitcnt vmcnt(0)
	s_and_saveexec_b64 s[16:17], s[0:1]
	s_cbranch_execz .LBB0_609
	s_mov_b64 s[34:35], exec
	v_mbcnt_lo_u32_b32 v0, s34, 0
	v_mbcnt_hi_u32_b32 v0, s35, v0
	v_cmp_eq_u32_e32 vcc, 0, v0
	s_and_b64 s[4:5], exec, vcc
	s_mov_b64 exec, s[4:5]
	s_cbranch_execz .LBB0_609
	s_bcnt1_i32_b64 s2, s[34:35]
	v_mov_b32_e32 v0, s2
	global_atomic_add v141, v0, s[20:21]
